# v83 + P4 per-item wave sum via 4 DPP adds + 2 permlane swap pairs instead of a 6-stage ds_bpermute butterfly
# baseline (speedup 1.0000x reference)
.LBB0_517:
	s_ashr_i32 s6, s16, 2
	s_add_i32 s7, s16, s27
	s_cmp_lt_i32 s7, s26
	s_cselect_b64 s[4:5], -1, 0
	s_waitcnt vmcnt(3)
	v_lshlrev_b32_e32 v21, 16, v15
	s_waitcnt vmcnt(2)
	v_lshlrev_b32_e32 v20, 16, v11
	v_and_b32_e32 v19, 0xffff0000, v15
	v_and_b32_e32 v18, 0xffff0000, v11
	v_lshlrev_b32_e32 v22, 16, v10
	v_and_b32_e32 v11, 0xffff0000, v14
	v_lshlrev_b32_e32 v15, 16, v13
	v_and_b32_e32 v24, 0xffff0000, v9
	v_lshlrev_b32_e32 v43, 16, v12
	s_and_b64 s[4:5], s[4:5], exec
	v_lshlrev_b32_e32 v23, 16, v14
	v_lshlrev_b32_e32 v14, 16, v9
	v_and_b32_e32 v25, 0xffff0000, v13
	v_and_b32_e32 v9, 0xffff0000, v12
	v_mul_f32_e32 v37, 0xbfb8aa3b, v22
	v_mov_b32_e32 v34, v19
	v_mov_b32_e32 v35, v11
	v_mul_f32_e32 v40, 0xbfb8aa3b, v24
	v_mul_f32_e32 v45, v15, v15
	v_mul_f32_e32 v46, v43, v43
	s_cselect_b32 s21, s7, s16
	v_mov_b32_e32 v12, v21
	v_mov_b32_e32 v13, v23
	v_exp_f32_e32 v37, v37
	v_pk_mul_f32 v[34:35], v[34:35], v[34:35]
	v_exp_f32_e32 v40, v40
	v_fmac_f32_e32 v45, v25, v25
	v_fmac_f32_e32 v46, v9, v9
	s_ashr_i32 s22, s21, 2
	v_and_b32_e32 v10, 0xffff0000, v10
	v_pk_fma_f32 v[12:13], v[12:13], v[12:13], v[34:35]
	v_add_f32_e32 v34, v46, v45
	s_ashr_i32 s23, s22, 31
	v_lshlrev_b32_e32 v42, 16, v8
	v_and_b32_e32 v8, 0xffff0000, v8
	v_mul_f32_e32 v36, 0xbfb8aa3b, v20
	v_mul_f32_e32 v38, 0xbfb8aa3b, v10
	v_mul_f32_e32 v39, 0xbfb8aa3b, v14
	v_add_f32_e32 v13, v13, v34
	s_mov_b32 s16, s7
	s_mul_hi_i32 s7, s22, 0x3000
	s_mul_i32 s24, s22, 0x3000
	s_lshl_b64 s[22:23], s[22:23], 12
	v_mul_f32_e32 v44, 0xbfb8aa3b, v8
	v_exp_f32_e32 v36, v36
	v_exp_f32_e32 v38, v38
	v_exp_f32_e32 v39, v39
	v_add_f32_e32 v13, v12, v13
	s_add_u32 s22, s8, s22
	v_exp_f32_e32 v44, v44
	v_add_f32_e32 v34, 1.0, v37
	v_add_f32_e32 v37, 1.0, v40
	s_addc_u32 s23, s9, s23
	s_lshl_b32 s21, s21, 10
	s_and_b32 s21, s21, 0xc00
	v_mul_f32_e32 v41, 0xbfb8aa3b, v42
	s_add_u32 s22, s22, s21
	v_exp_f32_e32 v41, v41
	v_add_f32_e32 v12, 1.0, v36
	v_add_f32_e32 v35, 1.0, v38
	v_add_f32_e32 v36, 1.0, v39
	s_addc_u32 s23, s23, 0
	v_add_f32_e32 v39, 1.0, v44
	v_rcp_f32_e32 v44, v34
	v_rcp_f32_e32 v46, v35
	v_rcp_f32_e32 v48, v36
	v_rcp_f32_e32 v50, v37
	global_load_dwordx4 v[34:37], v16, s[22:23] nt
	s_add_u32 s22, s10, s24
	s_waitcnt lgkmcnt(0)
	s_nop 1
	v_add_f32_dpp v13, v13, v13 quad_perm:[1,0,3,2] row_mask:0xf bank_mask:0xf
	s_addc_u32 s7, s11, s7
	s_add_u32 s22, s22, s21
	v_add_f32_e32 v38, 1.0, v41
	s_addc_u32 s23, s7, 0
	v_rcp_f32_e32 v52, v38
	v_rcp_f32_e32 v54, v39
	v_lshl_add_u64 v[38:39], s[22:23], 0, v[16:17]
	v_add_co_u32_e32 v38, vcc, s17, v38
	s_waitcnt lgkmcnt(0)
	s_nop 1
	v_add_f32_dpp v13, v13, v13 quad_perm:[2,3,0,1] row_mask:0xf bank_mask:0xf
	v_addc_co_u32_e32 v39, vcc, 0, v39, vcc
	global_load_dwordx4 v[38:41], v[38:39], off nt
	v_mul_f32_e32 v47, 0xbfb8aa3b, v18
	v_exp_f32_e32 v47, v47
	s_ashr_i32 s7, s6, 31
	s_lshl_b64 s[6:7], s[6:7], 12
	s_waitcnt lgkmcnt(0)
	s_nop 1
	v_add_f32_dpp v13, v13, v13 row_half_mirror row_mask:0xf bank_mask:0xf
	s_add_u32 s6, s12, s6
	s_addc_u32 s7, s13, s7
	s_and_b32 s21, s18, 0x600
	v_add_f32_e32 v56, 1.0, v47
	s_waitcnt lgkmcnt(0)
	s_nop 1
	v_add_f32_dpp v13, v13, v13 row_mirror row_mask:0xf bank_mask:0xf
	s_lshl_b32 s21, s21, 1
	s_add_u32 s22, s6, s21
	s_addc_u32 s23, s7, 0
	v_rcp_f32_e32 v12, v12
	s_waitcnt lgkmcnt(0)
	v_mov_b32_e32 v60, v13
	s_nop 1
	v_permlane16_swap_b32_e32 v60, v61
	s_nop 1
	v_permlane16_swap_b32_e32 v61, v60
	v_add_f32_e32 v13, v13, v61
	s_add_i32 s18, s18, s19
	s_waitcnt lgkmcnt(0)
	v_mov_b32_e32 v60, v13
	s_nop 1
	v_permlane32_swap_b32_e32 v60, v61
	s_nop 1
	v_permlane32_swap_b32_e32 v61, v60
	v_add_f32_e32 v13, v13, v61
	v_fmamk_f32 v13, v13, 0x3b000000, v32
	v_mul_f32_e32 v45, 0x4f800000, v13
	v_cmp_gt_f32_e32 vcc, s20, v13
	s_nop 1
	v_cndmask_b32_e32 v13, v13, v45, vcc
	v_sqrt_f32_e32 v45, v13
	s_nop 0
	v_add_u32_e32 v47, -1, v45
	v_add_u32_e32 v49, 1, v45
	v_fma_f32 v51, -v47, v45, v13
	v_fma_f32 v53, -v49, v45, v13
	v_cmp_ge_f32_e64 s[6:7], 0, v51
	s_nop 1
	v_cndmask_b32_e64 v45, v45, v47, s[6:7]
	v_cmp_lt_f32_e64 s[6:7], 0, v53
	s_nop 1
	v_cndmask_b32_e64 v45, v45, v49, s[6:7]
	v_mul_f32_e32 v47, 0x37800000, v45
	v_cndmask_b32_e32 v45, v45, v47, vcc
	v_cmp_class_f32_e32 vcc, v13, v33
	s_nop 1
	v_cndmask_b32_e32 v13, v45, v13, vcc
	v_div_scale_f32 v45, s[6:7], v13, v13, 1.0
	v_rcp_f32_e32 v49, v45
	v_div_scale_f32 v47, vcc, 1.0, v13, 1.0
	v_fma_f32 v51, -v45, v49, 1.0
	v_fmac_f32_e32 v49, v51, v49
	v_mul_f32_e32 v51, v47, v49
	v_fma_f32 v53, -v45, v51, v47
	v_fmac_f32_e32 v51, v53, v49
	v_fma_f32 v45, -v45, v51, v47
	v_div_fmas_f32 v45, v45, v49, v51
	v_div_fixup_f32 v53, v45, v13, 1.0
	v_pk_mul_f32 v[42:43], v[52:53], v[42:43]
	v_rcp_f32_e32 v52, v56
	v_mov_b32_e32 v47, v53
	v_mov_b32_e32 v13, v53
	v_mov_b32_e32 v55, v53
	v_mov_b32_e32 v49, v53
	v_pk_mul_f32 v[10:11], v[46:47], v[10:11]
	v_pk_mul_f32 v[12:13], v[12:13], v[20:21]
	v_mov_b32_e32 v51, v53
	v_mov_b32_e32 v45, v53
	v_pk_mul_f32 v[8:9], v[54:55], v[8:9]
	v_pk_mul_f32 v[14:15], v[48:49], v[14:15]
	s_waitcnt vmcnt(2)
	v_mul_f32_e32 v11, v5, v11
	v_mul_f32_e32 v13, v6, v13
	v_pk_mul_f32 v[24:25], v[50:51], v[24:25]
	v_pk_mul_f32 v[22:23], v[44:45], v[22:23]
	v_mul_f32_e32 v9, v1, v9
	v_mul_f32_e32 v15, v2, v15
	v_mul_f32_e32 v10, v10, v11
	v_mul_f32_e32 v11, v12, v13
	v_pk_mul_f32 v[12:13], v[52:53], v[18:19]
	v_mul_f32_e32 v43, v0, v43
	v_mul_f32_e32 v21, v3, v25
	v_mul_f32_e32 v23, v4, v23
	v_mul_f32_e32 v8, v8, v9
	v_mul_f32_e32 v9, v14, v15
	v_mul_f32_e32 v13, v7, v13
	v_mul_f32_e32 v20, v42, v43
	v_mul_f32_e32 v14, v24, v21
	v_mul_f32_e32 v15, v22, v23
	v_cvt_pk_bf16_f32 v8, v20, v8
	v_cvt_pk_bf16_f32 v9, v9, v14
	v_cvt_pk_bf16_f32 v10, v15, v10
	v_mul_f32_e32 v12, v12, v13
	v_cvt_pk_bf16_f32 v11, v11, v12
	global_store_dwordx4 v16, v[8:11], s[22:23]
	s_waitcnt vmcnt(2)
	v_mov_b64_e32 v[12:13], v[34:35]
	v_mov_b64_e32 v[14:15], v[36:37]
	s_waitcnt vmcnt(1)
	v_mov_b64_e32 v[8:9], v[38:39]
	v_mov_b64_e32 v[10:11], v[40:41]
	s_mov_b64 vcc, s[4:5]
	s_cbranch_vccnz .LBB0_517
